# GU tile order: row panels walked in groups of 4 (x8 column tiles per round) instead of 8 (x4), for L2 residency of the A panels
# speedup vs baseline: 1.0018x; 1.0018x over previous
;     __device__ bool next(int i, Unit& u) const {
;         const long L = (long)i * G + c; if (L >= nwg) return false;
;         int wgid = (int)L; { const int q = nwg / NXCD, r = nwg % NXCD, xcd = wgid % NXCD, off = wgid / NXCD; wgid = (xcd < r ? xcd * (q + 1) : r * (q + 1) + (xcd - r) * q) + off; }
;         const int nig = WGM * nN, gid = wgid / nig, fm = gid * WGM, gsz = (nM - fm) < WGM ? (nM - fm) : WGM;
;         u.pm = fm + ((wgid % nig) % gsz); u.pn = (wgid % nig) / gsz; return true;
; template <class Epi, bool ALIGN_EPI>
; __device__ __forceinline__ void gemm_phase(LAS unsigned char* lds, const Gemm g, const StaticOrder& S, const Epi& E, const int tid) {
;     const int wid = __builtin_amdgcn_readfirstlane(tid >> 6), lane = tid & 63, wr = wid >> 2, wc = wid & 3, fr = lane & 15, fq = lane >> 4;
;     const int K = g.K, nt = K / BK;
;     unsigned voffA[2], voffB[2];
; #pragma unroll
;     for (int i = 0; i < 2; ++i) { int R, C; stage_rc(tid * 16 + i * 8192, R, C); const int Rb = Epi::PERM ? ((R & ~31) + perm32(R & 31)) : R;
;         voffA[i] = (unsigned)(R * g.lda + C) * 2u; voffB[i] = (unsigned)(Rb * g.ldb + C) * 2u; }
;     const size_t kstep = (size_t)(BK * 2);
;     const size_t hA = (size_t)HALF * g.lda * 2, hB = (size_t)HALF * g.ldb * 2, tA = 2 * hA, tB = 2 * hB;
;     const unsigned ldsw = (unsigned)wid * 1024u;
;     const int aoff = lds_byte(wr * 64 + fr, fq * 8), boff = lds_byte(wc * 32 + fr, fq * 8);
;     ...
;     Unit cur, nxt; int ui = 0;
;     if (!S.next(0, cur)) return;
;     f32x4 acc[2][2][4][2];
; #pragma unroll
;     for (int a = 0; a < 2; ++a)
; #pragma unroll
;         for (int b = 0; b < 2; ++b)
; #pragma unroll
;             for (int m = 0; m < 4; ++m)
; #pragma unroll
;                 for (int n = 0; n < 2; ++n) acc[a][b][m][n] = (f32x4){0.f, 0.f, 0.f, 0.f};
;     bf16x8 At[4][2], B0[2][2], B1[2][2];
;     const char* cA = (const char*)g.A + (size_t)cur.pm * tA + (size_t)cur.pn * g.apn * 2; const char* cB = (const char*)g.Bt + (size_t)cur.pn * tB;
;     PG8_STAGE(PG8_SB(0, 0), cB, voffB); PG8_STAGE(PG8_SB(0, 1), cB + hB, voffB); PG8_STAGE(PG8_SA(0, 0), cA, voffA); PG8_STAGE(PG8_SA(0, 1), cA + hA, voffA);
.LBB0_294:
	s_cmp_ge_i32 s0, s38
	v_readfirstlane_b32 s8, v170
	s_cbranch_scc1 .LBB0_315
	v_lshlrev_b32_e32 v0, 4, v170
	s_waitcnt lgkmcnt(0)
	v_add_u32_e32 v1, 0x2000, v0
	v_ashrrev_i32_e32 v2, 31, v1
	v_lshrrev_b32_e32 v2, 22, v2
	v_add_u32_e32 v2, v1, v2
	v_ashrrev_i32_e32 v2, 10, v2
	v_mul_i32_i24_e32 v3, 0x400, v2
	v_sub_u32_e32 v1, v1, v3
	v_lshrrev_b32_e32 v3, 4, v1
	v_bitop3_b32 v1, v3, v1, 32 bitop3:0x6c
	v_ashrrev_i32_e32 v3, 31, v1
	v_lshrrev_b32_e32 v3, 26, v3
	v_add_u32_e32 v3, v1, v3
	s_waitcnt vmcnt(1)
	v_lshlrev_b32_e32 v5, 3, v2
	v_ashrrev_i32_e32 v4, 6, v3
	v_and_b32_e32 v5, -16, v5
	v_add_u32_e32 v5, v4, v5
	v_and_b32_e32 v3, 0xc0, v3
	v_and_b32_e32 v4, 3, v4
	s_mov_b32 s11, 0x7fffffe0
	v_lshrrev_b32_e32 v6, 2, v5
	v_lshlrev_b32_e32 v7, 1, v5
	v_sub_u32_e32 v1, v1, v3
	v_and_or_b32 v4, v5, s11, v4
	v_and_b32_e32 v6, 4, v6
	v_and_b32_e32 v7, 24, v7
	v_lshlrev_b32_e32 v2, 5, v2
	v_ashrrev_i16_sdwa v1, v235, sext(v1) dst_sel:DWORD dst_unused:UNUSED_PAD src0_sel:DWORD src1_sel:BYTE_0
	v_or3_b32 v4, v4, v6, v7
	v_and_b32_e32 v2, 32, v2
	v_bfe_i32 v3, v1, 0, 16
	v_mul_lo_u32 v4, s1, v4
	v_add_u32_e32 v1, v2, v3
	v_add_lshl_u32 v128, v4, v1, 1
	v_mul_lo_u32 v4, s25, v5
	v_add_lshl_u32 v130, v4, v1, 1
	v_bfe_i32 v1, v170, 27, 1
	v_lshrrev_b32_e32 v1, 22, v1
	v_add_u32_e32 v1, v0, v1
	v_and_b32_e32 v1, 0xfffffc00, v1
	v_sub_u32_e32 v0, v0, v1
	v_lshrrev_b32_e32 v1, 4, v0
	v_ashrrev_i32_e32 v6, 31, v170
	v_bitop3_b32 v0, v1, v0, 32 bitop3:0x6c
	v_lshrrev_b32_e32 v6, 26, v6
	v_ashrrev_i32_e32 v1, 31, v0
	v_add_u32_e32 v6, v170, v6
	v_lshrrev_b32_e32 v1, 26, v1
	v_ashrrev_i32_e32 v6, 6, v6
	v_add_u32_e32 v1, v0, v1
	v_lshlrev_b32_e32 v7, 3, v6
	v_ashrrev_i32_e32 v5, 6, v1
	v_and_b32_e32 v7, -16, v7
	v_add_u32_e32 v7, v5, v7
	v_and_b32_e32 v5, 3, v5
	s_ashr_i32 s47, s0, 31
	v_and_or_b32 v5, v7, s11, v5
	s_lshr_b32 s11, s47, 29
	s_add_i32 s11, s0, s11
	s_ashr_i32 s9, s8, 6
	s_lshl_b32 s94, s25, 8
	s_lshl_b32 s46, s7, 4
	s_ashr_i32 s39, s11, 3
	s_and_b32 s11, s11, -8
	s_ashr_i32 s10, s8, 8
	s_lshl_b32 s12, s1, 8
	s_lshl_b64 s[14:15], s[94:95], 1
	s_lshl_b32 s44, s1, 9
	s_lshl_b32 s45, s9, 10
	s_sub_i32 s11, s0, s11
	s_or_b32 s48, s46, 1
	s_cmp_lt_i32 s11, 0
	v_and_b32_e32 v1, 0xc0, v1
	s_cselect_b32 s40, s48, s46
	s_lshl_b32 s49, s7, 2
	v_lshrrev_b32_e32 v8, 2, v7
	v_lshlrev_b32_e32 v9, 1, v7
	v_sub_u32_e32 v0, v0, v1
	v_cvt_f32_u32_e32 v1, s49
	v_and_b32_e32 v8, 4, v8
	v_and_b32_e32 v9, 24, v9
	v_or3_b32 v5, v5, v8, v9
	v_mul_lo_u32 v8, s1, v5
	v_lshlrev_b32_e32 v5, 5, v6
	v_ashrrev_i16_sdwa v0, v235, sext(v0) dst_sel:DWORD dst_unused:UNUSED_PAD src0_sel:DWORD src1_sel:BYTE_0
	v_and_b32_e32 v5, 32, v5
	v_bfe_i32 v6, v0, 0, 16
	v_rcp_iflag_f32_e32 v1, v1
	v_add_u32_e32 v0, v5, v6
	v_mul_lo_u32 v7, s25, v7
	v_add_lshl_u32 v168, v8, v0, 1
	v_add_lshl_u32 v132, v7, v0, 1
	v_mov_b32_e32 v0, s11
	v_mul_i32_i24_e32 v0, s40, v0
	s_sub_i32 s41, 0, s49
	v_readfirstlane_b32 s11, v0
	v_mul_f32_e32 v0, 0x4f7ffffe, v1
	v_cvt_u32_f32_e32 v0, v0
	s_add_i32 s11, s11, s39
	s_abs_i32 s40, s11
	s_ashr_i32 s39, s11, 31
	v_readfirstlane_b32 s50, v0
	s_mul_i32 s41, s41, s50
	s_mul_hi_u32 s41, s50, s41
	s_add_i32 s50, s50, s41
	s_mul_hi_u32 s41, s40, s50
	s_mul_i32 s42, s41, s49
	s_sub_i32 s40, s40, s42
	s_add_i32 s42, s41, 1
	s_sub_i32 s43, s40, s49
	s_cmp_ge_u32 s40, s49
	s_cselect_b32 s41, s42, s41
	s_cselect_b32 s40, s43, s40
	s_add_i32 s42, s41, 1
	s_cmp_ge_u32 s40, s49
	s_cselect_b32 s40, s42, s41
	s_xor_b32 s40, s40, s39
	s_sub_i32 s39, s40, s39
	s_lshl_b32 s42, s39, 2
	s_sub_i32 s40, 0x80, s42
	s_min_i32 s43, s40, 4
	s_sext_i32_i16 s40, s43
	v_cvt_f32_i32_e32 v0, s40
	s_mul_i32 s39, s39, s49
	s_sub_i32 s11, s11, s39
	s_sext_i32_i16 s39, s11
	v_cvt_f32_i32_e32 v1, s39
	v_rcp_iflag_f32_e32 v8, v0
	s_xor_b32 s39, s39, s40
	s_ashr_i32 s39, s39, 30
	s_or_b32 s39, s39, 1
	v_mul_f32_e32 v8, v1, v8
	v_trunc_f32_e32 v8, v8
	v_fma_f32 v1, -v8, v0, v1
	v_cvt_i32_f32_e32 v8, v8
	v_cmp_ge_f32_e64 s[40:41], |v1|, |v0|
	s_and_b64 s[40:41], s[40:41], exec
	s_cselect_b32 s39, s39, 0
	v_readfirstlane_b32 s40, v8
	s_add_i32 s39, s40, s39
	s_mul_i32 s40, s39, s43
	s_sub_i32 s11, s11, s40
	s_sext_i32_i16 s11, s11
	s_add_i32 s64, s42, s11
	s_sext_i32_i16 s63, s39
	v_lshrrev_b32_e32 v194, 8, v170
	v_and_b32_e32 v195, 15, v170
	v_lshl_add_u32 v194, v194, 6, v195
	s_lshl_b32 s98, s64, 8
	v_add_u32_e32 v194, s98, v194
	v_lshlrev_b32_e32 v192, 3, v194
	v_mov_b32_e32 v193, 0
	v_lshl_add_u64 v[192:193], v[192:193], 0, s[26:27]
	global_load_dwordx2 v[176:177], v[192:193], off
	global_load_dwordx2 v[178:179], v[192:193], off offset:128
	global_load_dwordx2 v[180:181], v[192:193], off offset:256
	global_load_dwordx2 v[182:183], v[192:193], off offset:384
	global_load_dwordx2 v[184:185], v[192:193], off offset:1024
	global_load_dwordx2 v[186:187], v[192:193], off offset:1152
	global_load_dwordx2 v[188:189], v[192:193], off offset:1280
	global_load_dwordx2 v[190:191], v[192:193], off offset:1408
	s_ashr_i32 s11, s64, 31
	v_mov_b32_e32 v0, s63
	s_mul_i32 s11, s14, s11
	s_mul_hi_u32 s39, s14, s64
	v_mul_hi_i32_i24_e32 v9, s16, v0
	v_mul_i32_i24_e32 v8, s16, v0
	v_mul_hi_i32_i24_e32 v1, s44, v0
	v_mul_i32_i24_e32 v0, s44, v0
	s_add_i32 s11, s39, s11
	s_bfe_u32 s39, s25, 0x10017
	v_lshl_add_u64 v[144:145], s[22:23], 0, v[0:1]
	s_add_i32 s51, s45, 0
	s_mov_b32 s13, s95
	s_mul_i32 s39, s39, s64
	s_add_i32 m0, s51, 0x10000
	v_readfirstlane_b32 s42, v144
	v_readfirstlane_b32 s43, v145
	s_add_i32 s41, s11, s39
	s_mul_i32 s40, s14, s64
	v_lshl_add_u64 v[0:1], v[144:145], 0, s[12:13]
	v_lshl_add_u64 v[10:11], v[174:175], 0, s[40:41]
	v_readfirstlane_b32 s40, v0
	global_load_lds_dwordx4 v168, s[42:43]
	s_add_i32 m0, s51, 0x12000
	v_readfirstlane_b32 s41, v1
	global_load_lds_dwordx4 v128, s[42:43]
	s_add_i32 m0, s51, 0x14000
	v_lshl_add_u64 v[142:143], v[10:11], 0, v[8:9]
	s_add_i32 s52, s51, 0x2000
	s_nop 0
	global_load_lds_dwordx4 v168, s[40:41]
	s_add_i32 m0, s51, 0x16000
	v_lshl_add_u64 v[8:9], v[142:143], 0, s[94:95]
	global_load_lds_dwordx4 v128, s[40:41]
	v_readfirstlane_b32 s40, v142
	v_readfirstlane_b32 s41, v143
	s_mov_b32 m0, s51
	s_add_i32 s53, s51, 0x4000
	s_add_i32 s54, s51, 0x6000
	s_cmp_eq_u32 s10, 1
	s_nop 0
	global_load_lds_dwordx4 v132, s[40:41]
	s_mov_b32 m0, s52
	s_nop 0
	global_load_lds_dwordx4 v130, s[40:41]
	v_readfirstlane_b32 s40, v8
	v_readfirstlane_b32 s41, v9
	s_mov_b32 m0, s53
	s_nop 3
	global_load_lds_dwordx4 v132, s[40:41]
	s_mov_b32 m0, s54
	s_nop 0
	global_load_lds_dwordx4 v130, s[40:41]
	s_waitcnt vmcnt(8)
; __device__ __forceinline__ void load_rstd(float (&rsv)[2][4], const ssq_t* ssq, int row0) {
;     ...
; #pragma unroll
;     for (int ai = 0; ai < 2; ++ai)
; #pragma unroll
;         for (int m = 0; m < 4; ++m) rsv[ai][m] = __builtin_amdgcn_rsqf((float)t[ai][m] * (SSQ_INV / 1024.0f) + 1e-6f);
	v_ffbh_u32_e32 v194, v177
	v_min_u32_e32 v194, 32, v194
	v_lshlrev_b64 v[176:177], v194, v[176:177]
	v_min_u32_e32 v176, 1, v176
	v_or_b32_e32 v176, v177, v176
	v_cvt_f32_u32_e32 v176, v176
	v_sub_u32_e32 v194, 32, v194
	v_ldexp_f32 v176, v176, v194
	v_fmamk_f32 v176, v176, 0x30800000, v223
	v_rsq_f32_e32 v176, v176
	v_ffbh_u32_e32 v194, v179
	v_min_u32_e32 v194, 32, v194
	v_lshlrev_b64 v[178:179], v194, v[178:179]
	v_min_u32_e32 v178, 1, v178
	v_or_b32_e32 v178, v179, v178
	v_cvt_f32_u32_e32 v178, v178
	v_sub_u32_e32 v194, 32, v194
	v_ldexp_f32 v178, v178, v194
	v_fmamk_f32 v178, v178, 0x30800000, v223
	v_rsq_f32_e32 v178, v178
	v_ffbh_u32_e32 v194, v181
	v_min_u32_e32 v194, 32, v194
	v_lshlrev_b64 v[180:181], v194, v[180:181]
	v_min_u32_e32 v180, 1, v180
	v_or_b32_e32 v180, v181, v180
	v_cvt_f32_u32_e32 v180, v180
	v_sub_u32_e32 v194, 32, v194
	v_ldexp_f32 v180, v180, v194
	v_fmamk_f32 v180, v180, 0x30800000, v223
	v_rsq_f32_e32 v180, v180
	v_ffbh_u32_e32 v194, v183
	v_min_u32_e32 v194, 32, v194
	v_lshlrev_b64 v[182:183], v194, v[182:183]
	v_min_u32_e32 v182, 1, v182
	v_or_b32_e32 v182, v183, v182
	v_cvt_f32_u32_e32 v182, v182
	v_sub_u32_e32 v194, 32, v194
	v_ldexp_f32 v182, v182, v194
	v_fmamk_f32 v182, v182, 0x30800000, v223
	v_rsq_f32_e32 v182, v182
	v_ffbh_u32_e32 v194, v185
	v_min_u32_e32 v194, 32, v194
	v_lshlrev_b64 v[184:185], v194, v[184:185]
	v_min_u32_e32 v184, 1, v184
	v_or_b32_e32 v184, v185, v184
	v_cvt_f32_u32_e32 v184, v184
	v_sub_u32_e32 v194, 32, v194
	v_ldexp_f32 v184, v184, v194
	v_fmamk_f32 v184, v184, 0x30800000, v223
	v_rsq_f32_e32 v184, v184
	v_ffbh_u32_e32 v194, v187
	v_min_u32_e32 v194, 32, v194
	v_lshlrev_b64 v[186:187], v194, v[186:187]
	v_min_u32_e32 v186, 1, v186
	v_or_b32_e32 v186, v187, v186
	v_cvt_f32_u32_e32 v186, v186
	v_sub_u32_e32 v194, 32, v194
	v_ldexp_f32 v186, v186, v194
	v_fmamk_f32 v186, v186, 0x30800000, v223
	v_rsq_f32_e32 v186, v186
	v_ffbh_u32_e32 v194, v189
	v_min_u32_e32 v194, 32, v194
	v_lshlrev_b64 v[188:189], v194, v[188:189]
	v_min_u32_e32 v188, 1, v188
	v_or_b32_e32 v188, v189, v188
	v_cvt_f32_u32_e32 v188, v188
	v_sub_u32_e32 v194, 32, v194
	v_ldexp_f32 v188, v188, v194
	v_fmamk_f32 v188, v188, 0x30800000, v223
	v_rsq_f32_e32 v188, v188
	v_ffbh_u32_e32 v194, v191
	v_min_u32_e32 v194, 32, v194
	v_lshlrev_b64 v[190:191], v194, v[190:191]
	v_min_u32_e32 v190, 1, v190
	v_or_b32_e32 v190, v191, v190
	v_cvt_f32_u32_e32 v190, v190
	v_sub_u32_e32 v194, 32, v194
	v_ldexp_f32 v190, v190, v194
	v_fmamk_f32 v190, v190, 0x30800000, v223
	v_rsq_f32_e32 v190, v190
	v_mov_b32_e32 v172, v176
	v_mov_b32_e32 v173, v178
	v_mov_b32_e32 v236, v180
	v_mov_b32_e32 v237, v182
	v_mov_b32_e32 v238, v184
	v_mov_b32_e32 v239, v186
	v_mov_b32_e32 v230, v188
	v_mov_b32_e32 v231, v190
	v_mov_b32_e32 v254, s64
	s_cselect_b64 s[40:41], -1, 0
	s_cmp_lg_u32 s10, 1
	s_cbranch_scc1 .LBB0_297
	s_barrier

;     __device__ bool next(int i, Unit& u) const {
;         const long L = (long)i * G + c; if (L >= nwg) return false;
;         int wgid = (int)L; { const int q = nwg / NXCD, r = nwg % NXCD, xcd = wgid % NXCD, off = wgid / NXCD; wgid = (xcd < r ? xcd * (q + 1) : r * (q + 1) + (xcd - r) * q) + off; }
;         const int nig = WGM * nN, gid = wgid / nig, fm = gid * WGM, gsz = (nM - fm) < WGM ? (nM - fm) : WGM;
;         u.pm = fm + ((wgid % nig) % gsz); u.pn = (wgid % nig) / gsz; return true;
.LBB0_300:
	s_add_i32 s60, s60, 1
	s_mul_i32 s8, s60, s59
	s_mul_hi_u32 s9, s60, s6
	s_add_i32 s9, s9, s8
	s_mul_i32 s8, s60, s6
	s_add_u32 s8, s8, s0
	s_addc_u32 s9, s9, s47
	v_mov_b64_e32 v[224:225], s[38:39]
	v_cmp_ge_i64_e32 vcc, s[8:9], v[224:225]
	v_cmp_lt_i64_e64 s[10:11], s[8:9], v[224:225]
	s_cbranch_vccnz .LBB0_302
	s_and_b32 s8, s64, 3
	s_lshl_b32 s9, s63, 2
	s_add_i32 s8, s8, s9
	s_lshr_b32 s9, s6, 3
	s_add_i32 s8, s8, s9
	s_and_b32 s62, s64, -4
	s_sub_i32 s9, s8, s49
	s_cmp_ge_u32 s8, s49
	s_cselect_b32 s8, s9, s8
	s_cselect_b32 s9, 4, 0
	s_add_i32 s62, s62, s9
	s_lshr_b32 s61, s8, 2
	s_and_b32 s8, s8, 3
	s_add_i32 s62, s62, s8
	s_mov_b64 s[70:71], s[90:91]
